# barrier: everyone polls the global arrival counter (no release flag hop, no XCD relay)
# baseline (speedup 1.0000x reference)
; __device__ __forceinline__ unsigned xb_ld(unsigned* p)              { return __hip_atomic_load(p, __ATOMIC_RELAXED, __HIP_MEMORY_SCOPE_AGENT); }
; __device__ __forceinline__ unsigned xb_add(unsigned* p, unsigned v) { return __hip_atomic_fetch_add(p, v, __ATOMIC_RELAXED, __HIP_MEMORY_SCOPE_AGENT); }
; #define XB_SPIN(cond, bar) do { unsigned _sp = 0; while (cond) { __builtin_amdgcn_s_sleep(1); \
;     if ((++_sp & 255u) == 0u) { if (xb_ld(&(bar)[XB_TMO])) break; if (_sp > XB_SPIN_CAP) { atomicAdd(&(bar)[XB_TMO], 1u); break; } } } } while (0)
; __device__ __forceinline__ void xcd_barrier(const XcdBarrier& b) {
;     ...
;         const unsigned old = xb_add(&bar[XB_XSUB(b.x)], 1u);
;         const unsigned gen = old / nloc;
;         if (old + 1u == (gen + 1u) * nloc) {
;             __builtin_amdgcn_fence(__ATOMIC_RELEASE, "agent");
;             asm volatile("s_waitcnt vmcnt(0)" ::: "memory");
;             const unsigned og = xb_add(&bar[XB_TOP], 1u);
;             const unsigned tg = og / nx;
;             if (og + 1u == (tg + 1u) * nx) xb_add(&bar[XB_TOPGEN], 1u);
;             else XB_SPIN(xb_ld(&bar[XB_TOPGEN]) == tg, bar);
;             __builtin_amdgcn_fence(__ATOMIC_ACQUIRE, "agent");
;             xb_add(&bar[XB_XGEN(b.x)], 1u);
;             asm volatile("s_waitcnt vmcnt(0)" ::: "memory");
;         } else {
;             XB_SPIN(xb_ld(&bar[XB_XGEN(b.x)]) == gen, bar);
.LBB0_1974:
	s_lshl_b32 s24, s33, 6
	s_add_i32 s56, s24, 0x500
	s_lshl_b64 s[4:5], s[56:57], 2
	s_add_u32 s4, s2, s4
	s_addc_u32 s5, s3, s5
	v_mov_b64_e32 v[4:5], s[4:5]
	v_mov_b32_e32 v1, 1
	flat_atomic_add v3, v[4:5], v1 sc0
	v_cvt_f32_u32_e32 v1, v2
	v_sub_u32_e32 v4, 0, v2
	v_rcp_iflag_f32_e32 v1, v1
	s_nop 0
	v_mul_f32_e32 v1, 0x4f7ffffe, v1
	v_cvt_u32_f32_e32 v1, v1
	v_mul_lo_u32 v4, v4, v1
	v_mul_hi_u32 v4, v1, v4
	v_add_u32_e32 v1, v1, v4
	s_waitcnt vmcnt(0) lgkmcnt(0)
	v_mul_hi_u32 v1, v3, v1
	v_mul_lo_u32 v4, v1, v2
	v_sub_u32_e32 v4, v3, v4
	v_cmp_ge_u32_e32 vcc, v4, v2
	v_add_u32_e32 v5, 1, v1
	s_nop 0
	v_cndmask_b32_e32 v1, v1, v5, vcc
	v_sub_u32_e32 v5, v4, v2
	v_cndmask_b32_e32 v4, v4, v5, vcc
	v_cmp_ge_u32_e32 vcc, v4, v2
	v_add_u32_e32 v4, 1, v1
	s_nop 0
	v_cndmask_b32_e32 v1, v1, v4, vcc
	v_add_u32_e32 v4, 1, v3
	v_mad_u64_u32 v[2:3], s[4:5], v2, v1, v[2:3]
	v_cmp_ne_u32_e32 vcc, v4, v2
	s_and_saveexec_b64 s[4:5], vcc
	s_xor_b64 s[4:5], exec, s[4:5]
	s_cbranch_execz .LBB0_1987
	v_mad_u32_u24 v6, v1, v0, v0
	s_add_u32 s8, s2, 0x3400
	s_addc_u32 s9, s3, 0
	v_mov_b64_e32 v[2:3], s[8:9]
	flat_load_dword v0, v[2:3] sc1
	s_waitcnt vmcnt(0) lgkmcnt(0)
	v_cmp_lt_u32_e32 vcc, v0, v6
	s_and_saveexec_b64 s[6:7], vcc
	s_cbranch_execz .LBB0_1986
	s_mov_b32 s25, 1
	s_mov_b64 s[10:11], 0
	s_branch .LBB0_1978

.LBB0_1982:
	s_andn2_b64 s[14:15], s[14:15], exec
	s_and_b64 s[20:21], s[20:21], exec
	s_or_b64 s[14:15], s[14:15], s[20:21]
	s_and_saveexec_b64 s[20:21], s[18:19]
	s_cbranch_execz .LBB0_1977
	v_mov_b64_e32 v[2:3], s[8:9]
	flat_load_dword v0, v[2:3] sc1
	s_add_i32 s25, s25, 1
	s_or_b64 s[14:15], s[14:15], exec
	s_waitcnt vmcnt(0) lgkmcnt(0)
	v_cmp_ge_u32_e32 vcc, v0, v6
	s_orn2_b64 s[16:17], vcc, exec
	s_branch .LBB0_1977

; __device__ __forceinline__ unsigned xb_ld(unsigned* p)              { return __hip_atomic_load(p, __ATOMIC_RELAXED, __HIP_MEMORY_SCOPE_AGENT); }
; __device__ __forceinline__ unsigned xb_add(unsigned* p, unsigned v) { return __hip_atomic_fetch_add(p, v, __ATOMIC_RELAXED, __HIP_MEMORY_SCOPE_AGENT); }
; #define XB_SPIN(cond, bar) do { unsigned _sp = 0; while (cond) { __builtin_amdgcn_s_sleep(1); \
;     if ((++_sp & 255u) == 0u) { if (xb_ld(&(bar)[XB_TMO])) break; if (_sp > XB_SPIN_CAP) { atomicAdd(&(bar)[XB_TMO], 1u); break; } } } } while (0)
; __device__ __forceinline__ void xcd_barrier(const XcdBarrier& b) {
;     ...
;         if (old + 1u == (gen + 1u) * nloc) {
;             __builtin_amdgcn_fence(__ATOMIC_RELEASE, "agent");
;             asm volatile("s_waitcnt vmcnt(0)" ::: "memory");
;             const unsigned og = xb_add(&bar[XB_TOP], 1u);
;             const unsigned tg = og / nx;
;             if (og + 1u == (tg + 1u) * nx) xb_add(&bar[XB_TOPGEN], 1u);
;             else XB_SPIN(xb_ld(&bar[XB_TOPGEN]) == tg, bar);
.LBB0_1987:
	s_andn2_saveexec_b64 s[4:5], s[4:5]
	s_cbranch_execz .LBB0_2003
	v_mov_b32_e32 v1, s2
	v_add_co_u32_e32 v2, vcc, 0x3000, v1
	v_mov_b32_e32 v1, s3
	buffer_wbl2 sc1
	s_waitcnt vmcnt(0)
	v_addc_co_u32_e32 v3, vcc, 0, v1, vcc
	v_mov_b32_e32 v1, 1
	flat_atomic_add v1, v[2:3], v1 offset:1024 sc0
	v_cvt_f32_u32_e32 v2, v0
	v_sub_u32_e32 v3, 0, v0
	s_mov_b64 s[8:9], 0
	v_rcp_iflag_f32_e32 v2, v2
	s_nop 0
	v_mul_f32_e32 v2, 0x4f7ffffe, v2
	v_cvt_u32_f32_e32 v2, v2
	v_mul_lo_u32 v3, v3, v2
	v_mul_hi_u32 v3, v2, v3
	v_add_u32_e32 v2, v2, v3
	s_waitcnt vmcnt(0) lgkmcnt(0)
	v_mul_hi_u32 v2, v1, v2
	v_mul_lo_u32 v3, v2, v0
	v_sub_u32_e32 v3, v1, v3
	v_cmp_ge_u32_e32 vcc, v3, v0
	v_add_u32_e32 v4, 1, v2
	s_nop 0
	v_cndmask_b32_e32 v2, v2, v4, vcc
	v_sub_u32_e32 v4, v3, v0
	v_cndmask_b32_e32 v3, v3, v4, vcc
	v_cmp_ge_u32_e32 vcc, v3, v0
	v_add_u32_e32 v3, 1, v2
	s_nop 0
	v_cndmask_b32_e32 v2, v2, v3, vcc
	v_add_u32_e32 v3, 1, v1
	v_mad_u64_u32 v[0:1], s[4:5], v0, v2, v[0:1]
	s_add_u32 s4, s2, 0x3400
	s_addc_u32 s5, s3, 0
	v_cmp_ne_u32_e32 vcc, v3, v0
	v_mov_b32_e32 v6, v0
	v_mov_b64_e32 v[0:1], s[4:5]
	s_and_saveexec_b64 s[6:7], vcc
	s_cbranch_execz .LBB0_2000
	v_mov_b64_e32 v[0:1], s[4:5]
	flat_load_dword v0, v[0:1] sc1
	s_mov_b64 s[12:13], 0
	s_waitcnt vmcnt(0) lgkmcnt(0)
	v_cmp_lt_u32_e32 vcc, v0, v6
	s_and_saveexec_b64 s[10:11], vcc
	s_cbranch_execz .LBB0_1999
	s_add_u32 s8, s2, 0x200
	s_addc_u32 s9, s3, 0
	s_mov_b32 s25, 1
	s_branch .LBB0_1992

.LBB0_1997:
	v_mov_b64_e32 v[0:1], s[4:5]
	flat_load_dword v0, v[0:1] sc1
	s_add_i32 s25, s25, 1
	s_or_b64 s[18:19], s[18:19], exec
	s_waitcnt vmcnt(0) lgkmcnt(0)
	v_cmp_ge_u32_e32 vcc, v0, v6
	s_orn2_b64 s[16:17], vcc, exec
	s_branch .LBB0_1991

; __device__ __forceinline__ unsigned xb_ld(unsigned* p)              { return __hip_atomic_load(p, __ATOMIC_RELAXED, __HIP_MEMORY_SCOPE_AGENT); }
; __device__ __forceinline__ unsigned xb_add(unsigned* p, unsigned v) { return __hip_atomic_fetch_add(p, v, __ATOMIC_RELAXED, __HIP_MEMORY_SCOPE_AGENT); }
; #define XB_SPIN(cond, bar) do { unsigned _sp = 0; while (cond) { __builtin_amdgcn_s_sleep(1); \
;     if ((++_sp & 255u) == 0u) { if (xb_ld(&(bar)[XB_TMO])) break; if (_sp > XB_SPIN_CAP) { atomicAdd(&(bar)[XB_TMO], 1u); break; } } } } while (0)
; __device__ __forceinline__ void xcd_barrier(const XcdBarrier& b) {
;     ...
;             __builtin_amdgcn_fence(__ATOMIC_ACQUIRE, "agent");
;             xb_add(&bar[XB_XGEN(b.x)], 1u);
;             asm volatile("s_waitcnt vmcnt(0)" ::: "memory");
;         } else {
;             XB_SPIN(xb_ld(&bar[XB_XGEN(b.x)]) == gen, bar);
;             __builtin_amdgcn_fence(__ATOMIC_ACQUIRE, "agent");
;             asm volatile("s_waitcnt vmcnt(0)" ::: "memory");
;         }
;     }
;     __syncthreads();
.LBB0_2002:
	s_or_b64 exec, exec, s[4:5]
	s_waitcnt vmcnt(0) lgkmcnt(0)
	s_waitcnt vmcnt(0)
